# hand-written P1 mixer epilogue (EpiMix): z in place, conv taps as v_fmac_f32_dpp on pre-selected z/zp, packed f32 muls, running 64-bit store pointers; on top of peel + EpiGate + trim15
# baseline (speedup 1.0000x reference)
; __device__ __forceinline__ unsigned cvt_pk_bf16(float lo, float hi) { unsigned r; asm volatile("v_cvt_pk_bf16_f32 %0, %1, %2" : "=v"(r) : "v"(lo), "v"(hi)); return r; }
; __device__ __forceinline__ float dpp_ror1(float x) { return __int_as_float(__builtin_amdgcn_update_dpp(0, __float_as_int(x), 0x121, 0xF, 0xF, true)); }
; __device__ __forceinline__ float dpp_ror2(float x) { return __int_as_float(__builtin_amdgcn_update_dpp(0, __float_as_int(x), 0x122, 0xF, 0xF, true)); }
;     __device__ __forceinline__ void operator()(const f32x4 (&acc)[2][2][4][2], const Unit& u, int wr, int wc, int fr, int fq) const {
;         const int ch0 = u.pn * 64 + wc * 16 + 4 * fq;
;         const f32x4 w0 = *(const f32x4*)(cw + ch0), w1 = *(const f32x4*)(cw + ldw + ch0), w2 = *(const f32x4*)(cw + 2 * ldw + ch0);
;         const bool f1 = fr >= 1, f2 = fr >= 2;
; #pragma unroll
;         for (int ai = 0; ai < 2; ++ai) {
;             const int blk = u.pm * 4 + ai * 2 + wr;
;             f32x4 zp = {0.f, 0.f, 0.f, 0.f};
; #pragma unroll
;             for (int m = 0; m < 4; ++m) {
;                 const size_t row = (size_t)(u.pm * BM + ai * HALF + wr * 64 + m * 16 + fr);
;                 const f32x4 z = acc[ai][0][m][1] * acc[ai][1][m][0];
;                 f32x4 ya;
; #pragma unroll
;                 for (int i = 0; i < 4; ++i) {
;                     const float r1c = dpp_ror1(z[i]), r1p = dpp_ror1(zp[i]), r2c = dpp_ror2(z[i]), r2p = dpp_ror2(zp[i]);
;                     const float tm1 = f1 ? r1c : r1p, tm2 = f2 ? r2c : r2p;
;                     ya[i] = acc[ai][0][m][0][i] * (w0[i] * tm2 + w1[i] * tm1 + w2[i] * z[i]);
;                 }
;                 if (m == 0 && fr < 2) { *(f32x4*)(side + ((size_t)blk * 6 + 2 + fr) * ldu + ch0) = z; *(f32x4*)(side + ((size_t)blk * 6 + 4 + fr) * ldu + ch0) = acc[ai][0][0][0]; }
;                 else { u32x2 w; w.x = cvt_pk_bf16(ya[0], ya[1]); w.y = cvt_pk_bf16(ya[2], ya[3]); *(u32x2*)(MX + row * ldm + ch0) = w; }
;                 if (m == 3 && fr >= 14) *(f32x4*)(side + ((size_t)blk * 6 + (fr - 14)) * ldu + ch0) = z;
;                 { const f32x4 uu = acc[ai][1][m][1]; u32x2 w; w.x = cvt_pk_bf16(uu[0], uu[1]); w.y = cvt_pk_bf16(uu[2], uu[3]); *(u32x2*)(U + row * ldu + ch0) = w; }
;                 zp = z;
.LBB0_127:
	v_lshl_or_b32 v224, s15, 6, v183
	v_lshlrev_b32_e32 v225, 2, v224
	global_load_dwordx4 v[122:125], v225, s[42:43]
	global_load_dwordx4 v[126:129], v225, s[48:49]
	global_load_dwordx4 v[130:133], v225, s[50:51]
	v_readlane_b32 s62, v255, 42
	v_readlane_b32 s63, v255, 43
	s_mov_b32 s65, 0x100000
	v_and_b32_e32 v226, 15, v161
	v_cmp_eq_u32_e64 s[16:17], 15, v226
	v_lshl_add_u32 v227, s14, 8, v161
	v_mov_b32_e32 v177, 0
	v_lshlrev_b32_e32 v176, 13, v227
	v_lshl_add_u32 v176, v224, 1, v176
	v_lshl_add_u64 v[170:171], s[24:25], 0, v[176:177]
	v_lshlrev_b32_e32 v176, 12, v227
	v_lshl_add_u32 v176, v224, 1, v176
	v_lshl_add_u64 v[172:173], s[22:23], 0, v[176:177]
	s_lshl_b32 s14, s14, 2
	s_add_i32 s14, s14, s8
	s_mul_i32 s14, s14, 6
	v_add_u32_e32 v176, s14, v226
	v_lshlrev_b32_e32 v176, 13, v176
	v_lshl_add_u32 v176, v224, 2, v176
	v_lshl_add_u64 v[174:175], s[44:45], 0, v[176:177]
	s_mov_b64 s[28:29], exec
	s_waitcnt vmcnt(0)
	v_pk_mul_f32 v[134:135], v[138:139], v[134:135]
	v_pk_mul_f32 v[136:137], v[140:141], v[136:137]
	v_add_co_u32_e32 v176, vcc, 0x4000, v174
	v_addc_co_u32_e32 v177, vcc, 0, v175, vcc
	v_add_co_u32_e32 v178, vcc, 0x8000, v174
	v_addc_co_u32_e32 v179, vcc, 0, v175, vcc
	s_andn2_b64 exec, s[28:29], s[38:39]
	global_store_dwordx4 v[176:177], v[134:137], off
	global_store_dwordx4 v[178:179], v[118:121], off
	s_mov_b64 exec, s[28:29]
	s_nop 4
	v_pk_mul_f32 v[200:201], v[130:131], v[134:135]
	v_pk_mul_f32 v[202:203], v[132:133], v[136:137]
	v_fmac_f32_dpp v200, v134, v126 row_ror:1 row_mask:0xf bank_mask:0xf
	v_fmac_f32_dpp v201, v135, v127 row_ror:1 row_mask:0xf bank_mask:0xf
	v_fmac_f32_dpp v202, v136, v128 row_ror:1 row_mask:0xf bank_mask:0xf
	v_fmac_f32_dpp v203, v137, v129 row_ror:1 row_mask:0xf bank_mask:0xf
	v_fmac_f32_dpp v200, v134, v122 row_ror:2 row_mask:0xf bank_mask:0xf
	v_fmac_f32_dpp v201, v135, v123 row_ror:2 row_mask:0xf bank_mask:0xf
	v_fmac_f32_dpp v202, v136, v124 row_ror:2 row_mask:0xf bank_mask:0xf
	v_fmac_f32_dpp v203, v137, v125 row_ror:2 row_mask:0xf bank_mask:0xf
	v_pk_mul_f32 v[200:201], v[118:119], v[200:201]
	v_pk_mul_f32 v[202:203], v[120:121], v[202:203]
	v_cvt_pk_bf16_f32 v200, v200, v201
	v_cvt_pk_bf16_f32 v201, v202, v203
	v_cvt_pk_bf16_f32 v110, v110, v111
	v_cvt_pk_bf16_f32 v111, v112, v113
	s_and_b64 exec, s[28:29], s[38:39]
	global_store_dwordx2 v[170:171], v[200:201], off
	s_mov_b64 exec, s[28:29]
	global_store_dwordx2 v[172:173], v[110:111], off
	v_pk_mul_f32 v[106:107], v[114:115], v[106:107]
	v_pk_mul_f32 v[108:109], v[116:117], v[108:109]
	v_cndmask_b32_e64 v192, v106, v134, s[16:17]
	v_cndmask_b32_e64 v193, v107, v135, s[16:17]
	v_cndmask_b32_e64 v194, v108, v136, s[16:17]
	v_cndmask_b32_e64 v195, v109, v137, s[16:17]
	v_cndmask_b32_e64 v196, v106, v134, s[40:41]
	v_cndmask_b32_e64 v197, v107, v135, s[40:41]
	v_cndmask_b32_e64 v198, v108, v136, s[40:41]
	v_cndmask_b32_e64 v199, v109, v137, s[40:41]
	v_pk_mul_f32 v[204:205], v[130:131], v[106:107]
	v_pk_mul_f32 v[206:207], v[132:133], v[108:109]
	v_fmac_f32_dpp v204, v192, v126 row_ror:1 row_mask:0xf bank_mask:0xf
	v_fmac_f32_dpp v205, v193, v127 row_ror:1 row_mask:0xf bank_mask:0xf
	v_fmac_f32_dpp v206, v194, v128 row_ror:1 row_mask:0xf bank_mask:0xf
	v_fmac_f32_dpp v207, v195, v129 row_ror:1 row_mask:0xf bank_mask:0xf
	v_fmac_f32_dpp v204, v196, v122 row_ror:2 row_mask:0xf bank_mask:0xf
	v_fmac_f32_dpp v205, v197, v123 row_ror:2 row_mask:0xf bank_mask:0xf
	v_fmac_f32_dpp v206, v198, v124 row_ror:2 row_mask:0xf bank_mask:0xf
	v_fmac_f32_dpp v207, v199, v125 row_ror:2 row_mask:0xf bank_mask:0xf
	v_pk_mul_f32 v[204:205], v[102:103], v[204:205]
	v_pk_mul_f32 v[206:207], v[104:105], v[206:207]
	v_cvt_pk_bf16_f32 v204, v204, v205
	v_cvt_pk_bf16_f32 v205, v206, v207
	v_cvt_pk_bf16_f32 v94, v94, v95
	v_cvt_pk_bf16_f32 v95, v96, v97
	v_add_co_u32_e32 v170, vcc, 0x20000, v170
	v_addc_co_u32_e32 v171, vcc, 0, v171, vcc
	v_add_co_u32_e32 v172, vcc, 0x10000, v172
	v_addc_co_u32_e32 v173, vcc, 0, v173, vcc
	global_store_dwordx2 v[170:171], v[204:205], off
	global_store_dwordx2 v[172:173], v[94:95], off
	v_pk_mul_f32 v[90:91], v[98:99], v[90:91]
	v_pk_mul_f32 v[92:93], v[100:101], v[92:93]
	v_cndmask_b32_e64 v192, v90, v106, s[16:17]
	v_cndmask_b32_e64 v193, v91, v107, s[16:17]
	v_cndmask_b32_e64 v194, v92, v108, s[16:17]
	v_cndmask_b32_e64 v195, v93, v109, s[16:17]
	v_cndmask_b32_e64 v196, v90, v106, s[40:41]
	v_cndmask_b32_e64 v197, v91, v107, s[40:41]
	v_cndmask_b32_e64 v198, v92, v108, s[40:41]
	v_cndmask_b32_e64 v199, v93, v109, s[40:41]
	v_pk_mul_f32 v[200:201], v[130:131], v[90:91]
	v_pk_mul_f32 v[202:203], v[132:133], v[92:93]
	v_fmac_f32_dpp v200, v192, v126 row_ror:1 row_mask:0xf bank_mask:0xf
	v_fmac_f32_dpp v201, v193, v127 row_ror:1 row_mask:0xf bank_mask:0xf
	v_fmac_f32_dpp v202, v194, v128 row_ror:1 row_mask:0xf bank_mask:0xf
	v_fmac_f32_dpp v203, v195, v129 row_ror:1 row_mask:0xf bank_mask:0xf
	v_fmac_f32_dpp v200, v196, v122 row_ror:2 row_mask:0xf bank_mask:0xf
	v_fmac_f32_dpp v201, v197, v123 row_ror:2 row_mask:0xf bank_mask:0xf
	v_fmac_f32_dpp v202, v198, v124 row_ror:2 row_mask:0xf bank_mask:0xf
	v_fmac_f32_dpp v203, v199, v125 row_ror:2 row_mask:0xf bank_mask:0xf
	v_pk_mul_f32 v[200:201], v[86:87], v[200:201]
	v_pk_mul_f32 v[202:203], v[88:89], v[202:203]
	v_cvt_pk_bf16_f32 v200, v200, v201
	v_cvt_pk_bf16_f32 v201, v202, v203
	v_cvt_pk_bf16_f32 v78, v78, v79
	v_cvt_pk_bf16_f32 v79, v80, v81
	v_add_co_u32_e32 v170, vcc, 0x20000, v170
	v_addc_co_u32_e32 v171, vcc, 0, v171, vcc
	v_add_co_u32_e32 v172, vcc, 0x10000, v172
	v_addc_co_u32_e32 v173, vcc, 0, v173, vcc
	global_store_dwordx2 v[170:171], v[200:201], off
; __device__ __forceinline__ unsigned cvt_pk_bf16(float lo, float hi) { unsigned r; asm volatile("v_cvt_pk_bf16_f32 %0, %1, %2" : "=v"(r) : "v"(lo), "v"(hi)); return r; }
; __device__ __forceinline__ float dpp_ror1(float x) { return __int_as_float(__builtin_amdgcn_update_dpp(0, __float_as_int(x), 0x121, 0xF, 0xF, true)); }
; __device__ __forceinline__ float dpp_ror2(float x) { return __int_as_float(__builtin_amdgcn_update_dpp(0, __float_as_int(x), 0x122, 0xF, 0xF, true)); }
;     __device__ __forceinline__ void operator()(const f32x4 (&acc)[2][2][4][2], const Unit& u, int wr, int wc, int fr, int fq) const {
;         const int ch0 = u.pn * 64 + wc * 16 + 4 * fq;
;         const f32x4 w0 = *(const f32x4*)(cw + ch0), w1 = *(const f32x4*)(cw + ldw + ch0), w2 = *(const f32x4*)(cw + 2 * ldw + ch0);
;         const bool f1 = fr >= 1, f2 = fr >= 2;
; #pragma unroll
;         for (int ai = 0; ai < 2; ++ai) {
;             const int blk = u.pm * 4 + ai * 2 + wr;
;             f32x4 zp = {0.f, 0.f, 0.f, 0.f};
; #pragma unroll
;             for (int m = 0; m < 4; ++m) {
;                 const size_t row = (size_t)(u.pm * BM + ai * HALF + wr * 64 + m * 16 + fr);
;                 const f32x4 z = acc[ai][0][m][1] * acc[ai][1][m][0];
;                 f32x4 ya;
; #pragma unroll
;                 for (int i = 0; i < 4; ++i) {
;                     const float r1c = dpp_ror1(z[i]), r1p = dpp_ror1(zp[i]), r2c = dpp_ror2(z[i]), r2p = dpp_ror2(zp[i]);
;                     const float tm1 = f1 ? r1c : r1p, tm2 = f2 ? r2c : r2p;
;                     ya[i] = acc[ai][0][m][0][i] * (w0[i] * tm2 + w1[i] * tm1 + w2[i] * z[i]);
;                 }
;                 if (m == 0 && fr < 2) { *(f32x4*)(side + ((size_t)blk * 6 + 2 + fr) * ldu + ch0) = z; *(f32x4*)(side + ((size_t)blk * 6 + 4 + fr) * ldu + ch0) = acc[ai][0][0][0]; }
;                 else { u32x2 w; w.x = cvt_pk_bf16(ya[0], ya[1]); w.y = cvt_pk_bf16(ya[2], ya[3]); *(u32x2*)(MX + row * ldm + ch0) = w; }
;                 if (m == 3 && fr >= 14) *(f32x4*)(side + ((size_t)blk * 6 + (fr - 14)) * ldu + ch0) = z;
;                 { const f32x4 uu = acc[ai][1][m][1]; u32x2 w; w.x = cvt_pk_bf16(uu[0], uu[1]); w.y = cvt_pk_bf16(uu[2], uu[3]); *(u32x2*)(U + row * ldu + ch0) = w; }
;                 zp = z;
	global_store_dwordx2 v[172:173], v[78:79], off
	v_pk_mul_f32 v[74:75], v[82:83], v[74:75]
	v_pk_mul_f32 v[76:77], v[84:85], v[76:77]
	v_cndmask_b32_e64 v192, v74, v90, s[16:17]
	v_cndmask_b32_e64 v193, v75, v91, s[16:17]
	v_cndmask_b32_e64 v194, v76, v92, s[16:17]
	v_cndmask_b32_e64 v195, v77, v93, s[16:17]
	v_cndmask_b32_e64 v196, v74, v90, s[40:41]
	v_cndmask_b32_e64 v197, v75, v91, s[40:41]
	v_cndmask_b32_e64 v198, v76, v92, s[40:41]
	v_cndmask_b32_e64 v199, v77, v93, s[40:41]
	v_pk_mul_f32 v[204:205], v[130:131], v[74:75]
	v_pk_mul_f32 v[206:207], v[132:133], v[76:77]
	v_fmac_f32_dpp v204, v192, v126 row_ror:1 row_mask:0xf bank_mask:0xf
	v_fmac_f32_dpp v205, v193, v127 row_ror:1 row_mask:0xf bank_mask:0xf
	v_fmac_f32_dpp v206, v194, v128 row_ror:1 row_mask:0xf bank_mask:0xf
	v_fmac_f32_dpp v207, v195, v129 row_ror:1 row_mask:0xf bank_mask:0xf
	v_fmac_f32_dpp v204, v196, v122 row_ror:2 row_mask:0xf bank_mask:0xf
	v_fmac_f32_dpp v205, v197, v123 row_ror:2 row_mask:0xf bank_mask:0xf
	v_fmac_f32_dpp v206, v198, v124 row_ror:2 row_mask:0xf bank_mask:0xf
	v_fmac_f32_dpp v207, v199, v125 row_ror:2 row_mask:0xf bank_mask:0xf
	v_pk_mul_f32 v[204:205], v[70:71], v[204:205]
	v_pk_mul_f32 v[206:207], v[72:73], v[206:207]
	v_cvt_pk_bf16_f32 v204, v204, v205
	v_cvt_pk_bf16_f32 v205, v206, v207
	v_cvt_pk_bf16_f32 v66, v66, v67
	v_cvt_pk_bf16_f32 v67, v68, v69
	v_add_co_u32_e32 v170, vcc, 0x20000, v170
	v_addc_co_u32_e32 v171, vcc, 0, v171, vcc
	v_add_co_u32_e32 v172, vcc, 0x10000, v172
	v_addc_co_u32_e32 v173, vcc, 0, v173, vcc
	global_store_dwordx2 v[170:171], v[204:205], off
	global_store_dwordx2 v[172:173], v[66:67], off
	v_add_co_u32_e32 v176, vcc, 0xfffe4000, v174
	v_addc_co_u32_e32 v177, vcc, -1, v175, vcc
	s_and_b64 exec, s[28:29], s[40:41]
	global_store_dwordx4 v[176:177], v[74:77], off
	s_mov_b64 exec, s[28:29]
	v_pk_mul_f32 v[58:59], v[62:63], v[58:59]
	v_pk_mul_f32 v[60:61], v[64:65], v[60:61]
	v_add_co_u32_e32 v176, vcc, 0x1c000, v174
	v_addc_co_u32_e32 v177, vcc, 0, v175, vcc
	v_add_co_u32_e32 v178, vcc, 0x20000, v174
	v_addc_co_u32_e32 v179, vcc, 0, v175, vcc
	s_andn2_b64 exec, s[28:29], s[38:39]
	global_store_dwordx4 v[176:177], v[58:61], off
	global_store_dwordx4 v[178:179], v[54:57], off
	s_mov_b64 exec, s[28:29]
	s_nop 4
	v_pk_mul_f32 v[200:201], v[130:131], v[58:59]
	v_pk_mul_f32 v[202:203], v[132:133], v[60:61]
	v_fmac_f32_dpp v200, v58, v126 row_ror:1 row_mask:0xf bank_mask:0xf
	v_fmac_f32_dpp v201, v59, v127 row_ror:1 row_mask:0xf bank_mask:0xf
	v_fmac_f32_dpp v202, v60, v128 row_ror:1 row_mask:0xf bank_mask:0xf
	v_fmac_f32_dpp v203, v61, v129 row_ror:1 row_mask:0xf bank_mask:0xf
	v_fmac_f32_dpp v200, v58, v122 row_ror:2 row_mask:0xf bank_mask:0xf
	v_fmac_f32_dpp v201, v59, v123 row_ror:2 row_mask:0xf bank_mask:0xf
	v_fmac_f32_dpp v202, v60, v124 row_ror:2 row_mask:0xf bank_mask:0xf
	v_fmac_f32_dpp v203, v61, v125 row_ror:2 row_mask:0xf bank_mask:0xf
	v_pk_mul_f32 v[200:201], v[54:55], v[200:201]
	v_pk_mul_f32 v[202:203], v[56:57], v[202:203]
	v_cvt_pk_bf16_f32 v200, v200, v201
	v_cvt_pk_bf16_f32 v201, v202, v203
	v_cvt_pk_bf16_f32 v46, v46, v47
	v_cvt_pk_bf16_f32 v47, v48, v49
	v_add_co_u32_e32 v170, vcc, 0xa0000, v170
	v_addc_co_u32_e32 v171, vcc, 0, v171, vcc
	v_add_co_u32_e32 v172, vcc, 0x50000, v172
	v_addc_co_u32_e32 v173, vcc, 0, v173, vcc
	s_and_b64 exec, s[28:29], s[38:39]
	global_store_dwordx2 v[170:171], v[200:201], off
	s_mov_b64 exec, s[28:29]
	global_store_dwordx2 v[172:173], v[46:47], off
	v_pk_mul_f32 v[42:43], v[50:51], v[42:43]
	v_pk_mul_f32 v[44:45], v[52:53], v[44:45]
	v_cndmask_b32_e64 v192, v42, v58, s[16:17]
	v_cndmask_b32_e64 v193, v43, v59, s[16:17]
	v_cndmask_b32_e64 v194, v44, v60, s[16:17]
	v_cndmask_b32_e64 v195, v45, v61, s[16:17]
	v_cndmask_b32_e64 v196, v42, v58, s[40:41]
	v_cndmask_b32_e64 v197, v43, v59, s[40:41]
	v_cndmask_b32_e64 v198, v44, v60, s[40:41]
	v_cndmask_b32_e64 v199, v45, v61, s[40:41]
	v_pk_mul_f32 v[204:205], v[130:131], v[42:43]
	v_pk_mul_f32 v[206:207], v[132:133], v[44:45]
	v_fmac_f32_dpp v204, v192, v126 row_ror:1 row_mask:0xf bank_mask:0xf
	v_fmac_f32_dpp v205, v193, v127 row_ror:1 row_mask:0xf bank_mask:0xf
	v_fmac_f32_dpp v206, v194, v128 row_ror:1 row_mask:0xf bank_mask:0xf
	v_fmac_f32_dpp v207, v195, v129 row_ror:1 row_mask:0xf bank_mask:0xf
; __device__ __forceinline__ unsigned cvt_pk_bf16(float lo, float hi) { unsigned r; asm volatile("v_cvt_pk_bf16_f32 %0, %1, %2" : "=v"(r) : "v"(lo), "v"(hi)); return r; }
; __device__ __forceinline__ float dpp_ror1(float x) { return __int_as_float(__builtin_amdgcn_update_dpp(0, __float_as_int(x), 0x121, 0xF, 0xF, true)); }
; #define PG8_BAR __builtin_amdgcn_s_barrier()
;     __device__ __forceinline__ void operator()(const f32x4 (&acc)[2][2][4][2], const Unit& u, int wr, int wc, int fr, int fq) const {
;     ...
;             for (int m = 0; m < 4; ++m) {
;                 const size_t row = (size_t)(u.pm * BM + ai * HALF + wr * 64 + m * 16 + fr);
;                 const f32x4 z = acc[ai][0][m][1] * acc[ai][1][m][0];
;                 f32x4 ya;
; #pragma unroll
;                 for (int i = 0; i < 4; ++i) {
;                     const float r1c = dpp_ror1(z[i]), r1p = dpp_ror1(zp[i]), r2c = dpp_ror2(z[i]), r2p = dpp_ror2(zp[i]);
;                     const float tm1 = f1 ? r1c : r1p, tm2 = f2 ? r2c : r2p;
;                     ya[i] = acc[ai][0][m][0][i] * (w0[i] * tm2 + w1[i] * tm1 + w2[i] * z[i]);
;                 }
;                 if (m == 0 && fr < 2) { *(f32x4*)(side + ((size_t)blk * 6 + 2 + fr) * ldu + ch0) = z; *(f32x4*)(side + ((size_t)blk * 6 + 4 + fr) * ldu + ch0) = acc[ai][0][0][0]; }
;                 else { u32x2 w; w.x = cvt_pk_bf16(ya[0], ya[1]); w.y = cvt_pk_bf16(ya[2], ya[3]); *(u32x2*)(MX + row * ldm + ch0) = w; }
;                 if (m == 3 && fr >= 14) *(f32x4*)(side + ((size_t)blk * 6 + (fr - 14)) * ldu + ch0) = z;
;                 { const f32x4 uu = acc[ai][1][m][1]; u32x2 w; w.x = cvt_pk_bf16(uu[0], uu[1]); w.y = cvt_pk_bf16(uu[2], uu[3]); *(u32x2*)(U + row * ldu + ch0) = w; }
;                 zp = z;
; template <class Epi, class Sched, bool ALIGN_EPI = false, bool SP2 = false>
; __device__ __forceinline__ void gemm_phase(PG8_LAS unsigned char* lds, const Gemm g, const Sched& S, const Epi& E) {
;     ...
;         if (!has_next) break;
; #pragma unroll
;         for (int a = 0; a < 2; ++a)
; #pragma unroll
;             for (int b = 0; b < 2; ++b)
; #pragma unroll
;                 for (int m = 0; m < 4; ++m)
; #pragma unroll
;                     for (int n = 0; n < 2; ++n) acc[a][b][m][n] = (f32x4){0.f, 0.f, 0.f, 0.f};
;         cur = nxt; cA = nA; cB = nB; ++ui;
;         if constexpr (ALIGN_EPI) { if (wr == 1) PG8_BAR; }
	v_fmac_f32_dpp v204, v196, v122 row_ror:2 row_mask:0xf bank_mask:0xf
	v_fmac_f32_dpp v205, v197, v123 row_ror:2 row_mask:0xf bank_mask:0xf
	v_fmac_f32_dpp v206, v198, v124 row_ror:2 row_mask:0xf bank_mask:0xf
	v_fmac_f32_dpp v207, v199, v125 row_ror:2 row_mask:0xf bank_mask:0xf
	v_pk_mul_f32 v[204:205], v[38:39], v[204:205]
	v_pk_mul_f32 v[206:207], v[40:41], v[206:207]
	v_cvt_pk_bf16_f32 v204, v204, v205
	v_cvt_pk_bf16_f32 v205, v206, v207
	v_cvt_pk_bf16_f32 v30, v30, v31
	v_cvt_pk_bf16_f32 v31, v32, v33
	v_add_co_u32_e32 v170, vcc, 0x20000, v170
	v_addc_co_u32_e32 v171, vcc, 0, v171, vcc
	v_add_co_u32_e32 v172, vcc, 0x10000, v172
	v_addc_co_u32_e32 v173, vcc, 0, v173, vcc
	global_store_dwordx2 v[170:171], v[204:205], off
	global_store_dwordx2 v[172:173], v[30:31], off
	v_pk_mul_f32 v[26:27], v[34:35], v[26:27]
	v_pk_mul_f32 v[28:29], v[36:37], v[28:29]
	v_cndmask_b32_e64 v192, v26, v42, s[16:17]
	v_cndmask_b32_e64 v193, v27, v43, s[16:17]
	v_cndmask_b32_e64 v194, v28, v44, s[16:17]
	v_cndmask_b32_e64 v195, v29, v45, s[16:17]
	v_cndmask_b32_e64 v196, v26, v42, s[40:41]
	v_cndmask_b32_e64 v197, v27, v43, s[40:41]
	v_cndmask_b32_e64 v198, v28, v44, s[40:41]
	v_cndmask_b32_e64 v199, v29, v45, s[40:41]
	v_pk_mul_f32 v[200:201], v[130:131], v[26:27]
	v_pk_mul_f32 v[202:203], v[132:133], v[28:29]
	v_fmac_f32_dpp v200, v192, v126 row_ror:1 row_mask:0xf bank_mask:0xf
	v_fmac_f32_dpp v201, v193, v127 row_ror:1 row_mask:0xf bank_mask:0xf
	v_fmac_f32_dpp v202, v194, v128 row_ror:1 row_mask:0xf bank_mask:0xf
	v_fmac_f32_dpp v203, v195, v129 row_ror:1 row_mask:0xf bank_mask:0xf
	v_fmac_f32_dpp v200, v196, v122 row_ror:2 row_mask:0xf bank_mask:0xf
	v_fmac_f32_dpp v201, v197, v123 row_ror:2 row_mask:0xf bank_mask:0xf
	v_fmac_f32_dpp v202, v198, v124 row_ror:2 row_mask:0xf bank_mask:0xf
	v_fmac_f32_dpp v203, v199, v125 row_ror:2 row_mask:0xf bank_mask:0xf
	v_pk_mul_f32 v[200:201], v[22:23], v[200:201]
	v_pk_mul_f32 v[202:203], v[24:25], v[202:203]
	v_cvt_pk_bf16_f32 v200, v200, v201
	v_cvt_pk_bf16_f32 v201, v202, v203
	v_cvt_pk_bf16_f32 v14, v14, v15
	v_cvt_pk_bf16_f32 v15, v16, v17
	v_add_co_u32_e32 v170, vcc, 0x20000, v170
	v_addc_co_u32_e32 v171, vcc, 0, v171, vcc
	v_add_co_u32_e32 v172, vcc, 0x10000, v172
	v_addc_co_u32_e32 v173, vcc, 0, v173, vcc
	global_store_dwordx2 v[170:171], v[200:201], off
	global_store_dwordx2 v[172:173], v[14:15], off
	v_pk_mul_f32 v[10:11], v[18:19], v[10:11]
	v_pk_mul_f32 v[12:13], v[20:21], v[12:13]
	v_cndmask_b32_e64 v192, v10, v26, s[16:17]
	v_cndmask_b32_e64 v193, v11, v27, s[16:17]
	v_cndmask_b32_e64 v194, v12, v28, s[16:17]
	v_cndmask_b32_e64 v195, v13, v29, s[16:17]
	v_cndmask_b32_e64 v196, v10, v26, s[40:41]
	v_cndmask_b32_e64 v197, v11, v27, s[40:41]
	v_cndmask_b32_e64 v198, v12, v28, s[40:41]
	v_cndmask_b32_e64 v199, v13, v29, s[40:41]
	v_pk_mul_f32 v[204:205], v[130:131], v[10:11]
	v_pk_mul_f32 v[206:207], v[132:133], v[12:13]
	v_fmac_f32_dpp v204, v192, v126 row_ror:1 row_mask:0xf bank_mask:0xf
	v_fmac_f32_dpp v205, v193, v127 row_ror:1 row_mask:0xf bank_mask:0xf
	v_fmac_f32_dpp v206, v194, v128 row_ror:1 row_mask:0xf bank_mask:0xf
	v_fmac_f32_dpp v207, v195, v129 row_ror:1 row_mask:0xf bank_mask:0xf
	v_fmac_f32_dpp v204, v196, v122 row_ror:2 row_mask:0xf bank_mask:0xf
	v_fmac_f32_dpp v205, v197, v123 row_ror:2 row_mask:0xf bank_mask:0xf
	v_fmac_f32_dpp v206, v198, v124 row_ror:2 row_mask:0xf bank_mask:0xf
	v_fmac_f32_dpp v207, v199, v125 row_ror:2 row_mask:0xf bank_mask:0xf
	v_pk_mul_f32 v[204:205], v[6:7], v[204:205]
	v_pk_mul_f32 v[206:207], v[8:9], v[206:207]
	v_cvt_pk_bf16_f32 v204, v204, v205
	v_cvt_pk_bf16_f32 v205, v206, v207
	v_cvt_pk_bf16_f32 v2, v2, v3
	v_cvt_pk_bf16_f32 v3, v4, v5
	v_add_co_u32_e32 v170, vcc, 0x20000, v170
	v_addc_co_u32_e32 v171, vcc, 0, v171, vcc
	v_add_co_u32_e32 v172, vcc, 0x10000, v172
	v_addc_co_u32_e32 v173, vcc, 0, v173, vcc
	global_store_dwordx2 v[170:171], v[204:205], off
	global_store_dwordx2 v[172:173], v[2:3], off
	v_add_co_u32_e32 v176, vcc, 0xffffc000, v174
	v_addc_co_u32_e32 v177, vcc, -1, v175, vcc
	s_and_b64 exec, s[28:29], s[40:41]
	global_store_dwordx4 v[176:177], v[10:13], off
	s_mov_b64 exec, s[28:29]
	s_andn2_b64 vcc, exec, s[56:57]
	s_mov_b64 s[26:27], -1
	s_cbranch_vccnz .LBB0_113
	s_andn2_b64 vcc, exec, s[20:21]
	s_cbranch_vccnz .LBB0_112
	s_barrier
	s_branch .LBB0_112
